# in-proj/ff1 first tile: K-slice 1 requested before waiting for K-slice 0 (first-tile flag in s100, counted vmcnt(8)); on v196
# speedup vs baseline: 1.0006x; 1.0006x over previous
; #define WAIT_V0() asm volatile("s_waitcnt vmcnt(0)" ::: "memory")
; #define G_LANE_SETUP() \
;     int tid_ = threadIdx.x; \
;     asm volatile("" : "+v"(tid_));    \
;     const int wid = tid_ >> 6, lane = tid_ & 63, wr = wid >> 2, wc = wid & 3, fr = lane & 15, fq = lane >> 4; \
;     unsigned soff[4];        \
;     _Pragma("unroll") for (int i = 0; i < 4; ++i) { int sR, sC; stage_rc2(wid * 1024 + i * 8192 + lane * 16, sR, sC); soff[i] = (unsigned)(sR * K + sC) * 2u; }
; template <int EK>
; DI void gemm_stream(const Params& p, int l, const bf16_t* __restrict__ A, const bf16_t* __restrict__ Bt, int M, int N, int K, ldsp_t shm) {
;     const int nM = M / 256, nN = N / 256, nwg = nM * nN;
;     int L = blockIdx.x;
;     if (L >= nwg) return;
;     ...
;     const int nt = K / 64;
;     int pm, pn;
;     tile_coords(L, nM, nN, pm, pn);
;     const bf16_t* Ab = A + (size_t)pm * 256 * K;
;     const bf16_t* Bb = Bt + (size_t)pn * 256 * K;
;     { G_LANE_SETUP(); (void)wr; (void)wc; (void)fr; (void)fq; G_STAGE(Ab, Bb, 0, 0); WAIT_V0(); __syncthreads(); }
; DI void run_phase(const Params& p, int ph, ldsp_t smem) {
;     if (ph == 0) { phase0(p, smem); return; }
;     if (ph == 1) { phase1(p); return; }
;     const int l = (ph - 2) / 5, k = (ph - 2) % 5;
;     const bool last = l == DEPTH - 1;
;     switch (k) {
;         case 0: gemm_stream<0>(p, l, p.H, p.wt_in + (size_t)l * IN_DIM * DM, NTOK, IN_DIM, DM, smem); break;
;         case 1: mixer_phase(p, l, smem); break;
;         case 2: gemm_stream<1>(p, l, p.MIX, p.wt_out + (size_t)l * DM * DM, NLAT, DM, DM, smem);
;                 if (!last) ctx_tiles<1, 64, 8>(p, l, p.MIX + (size_t)NLAT * DM, p.wt_out + (size_t)l * DM * DM, DM, DM, smem);
;                 break;
;         case 3: gemm_stream<2>(p, l, p.H, p.wt_ff1 + (size_t)l * FF * DM, NLAT, FF, DM, smem);
.LBB0_98:
	s_add_i32 s4, s93, -2
	s_mul_hi_i32 s5, s4, 0x66666667
	s_lshr_b32 s6, s5, 31
	s_ashr_i32 s5, s5, 1
	s_add_i32 s48, s5, s6
	s_mul_i32 s5, s48, 5
	s_sub_i32 s44, s4, s5
	s_sub_i32 s4, s93, 17
	s_cmp_lt_u32 s4, 5
	v_writelane_b32 v255, s5, 4
	s_cselect_b64 s[4:5], -1, 0
	v_writelane_b32 v255, s4, 5
	s_mov_b64 s[6:7], 0
	s_cmp_lt_i32 s44, 2
	v_writelane_b32 v255, s5, 6
	v_writelane_b32 v255, s6, 7
	s_mov_b64 s[4:5], -1
	s_nop 0
	v_writelane_b32 v255, s7, 8
	v_writelane_b32 v255, s93, 9
	s_cbranch_scc1 .LBB0_159
	v_readlane_b32 s12, v254, 45
	s_cmp_gt_i32 s44, 2
	v_readlane_b32 s13, v254, 46
	s_movk_i32 s15, 0x70
	s_cbranch_scc0 .LBB0_116
	s_cmp_eq_u32 s44, 3
	s_mov_b64 s[18:19], 0x400
	s_movk_i32 s90, 0x8000
	s_cbranch_scc0 .LBB0_121
	s_ashr_i32 s49, s48, 31
	s_lshl_b64 s[4:5], s[48:49], 23
	v_readlane_b32 s6, v253, 22
	s_add_u32 s9, s60, s4
	v_readlane_b32 s7, v253, 23
	s_addc_u32 s45, s61, s5
	s_andn2_b64 vcc, exec, s[6:7]
	v_readlane_b32 s8, v253, 24
	v_readlane_b32 s14, v253, 25
	s_movk_i32 s20, 0x7800
	s_mov_b64 s[22:23], 0x300
	s_mov_b64 s[24:25], 0x500
	s_mov_b64 s[26:27], 0x700
	s_cbranch_vccnz .LBB0_117
	v_mov_b32_e32 v0, v252
	v_readlane_b32 s38, v253, 45
	v_lshlrev_b32_e32 v1, 4, v0
	v_and_b32_e32 v3, 32, v0
	v_and_b32_e32 v2, 0xfffffc00, v1
	v_bitop3_b32 v3, v1, v3, 48 bitop3:0x6c
	s_waitcnt lgkmcnt(0)
	v_add_u32_e32 v5, 0x2000, v1
	v_add_u32_e32 v6, 0x4000, v1
	v_add_u32_e32 v1, 0x6000, v1
	v_bfe_u32 v4, v0, 2, 4
	v_and_or_b32 v3, v0, 64, v3
	v_lshrrev_b32_e32 v0, 3, v0
	v_lshrrev_b32_e32 v5, 7, v5
	v_lshrrev_b32_e32 v6, 7, v6
	v_lshrrev_b32_e32 v1, 7, v1
	v_and_or_b32 v0, v0, s86, v4
	v_and_or_b32 v5, v5, s86, v4
	v_and_or_b32 v6, v6, s86, v4
	v_and_or_b32 v1, v1, s86, v4
	v_lshl_or_b32 v0, v0, 11, v3
	v_lshl_or_b32 v5, v5, 11, v3
	v_lshl_or_b32 v6, v6, 11, v3
	v_lshl_or_b32 v1, v1, 11, v3
	v_add_u32_e32 v3, 0x8000, v2
	v_readfirstlane_b32 s10, v2
	v_readlane_b32 s16, v253, 49
	v_readlane_b32 s39, v253, 46
	s_add_u32 s6, s9, s38
	s_mov_b32 m0, s10
	v_readlane_b32 s17, v253, 50
	v_readfirstlane_b32 s10, v3
	s_addc_u32 s7, s45, s39
	v_readlane_b32 s40, v253, 47
	v_readlane_b32 s50, v253, 51
	v_readlane_b32 s41, v253, 48
	global_load_lds_dwordx4 v0, s[16:17]
	s_mov_b32 m0, s10
	v_readlane_b32 s47, v253, 0
	global_load_lds_dwordx4 v0, s[6:7]
	v_add_u32_e32 v0, 0x2000, v2
	s_nop 0
	v_readfirstlane_b32 s10, v0
	v_add_u32_e32 v0, 0xa000, v2
	s_mov_b32 m0, s10
	v_readfirstlane_b32 s10, v0
	v_add_u32_e32 v0, 0x4000, v2
	global_load_lds_dwordx4 v5, s[16:17]
	s_mov_b32 m0, s10
	v_readfirstlane_b32 s10, v0
	v_add_u32_e32 v0, 0xc000, v2
	global_load_lds_dwordx4 v5, s[6:7]
	s_mov_b32 m0, s10
	v_readfirstlane_b32 s10, v0
	v_add_u32_e32 v0, 0x6000, v2
	global_load_lds_dwordx4 v6, s[16:17]
	s_mov_b32 m0, s10
	v_readfirstlane_b32 s10, v0
	v_add_u32_e32 v0, 0xe000, v2
	global_load_lds_dwordx4 v6, s[6:7]
	s_mov_b32 m0, s10
	v_readfirstlane_b32 s10, v0
	global_load_lds_dwordx4 v1, s[16:17]
	s_mov_b32 m0, s10
	s_nop 0
	global_load_lds_dwordx4 v1, s[6:7]
	s_lshl_b32 s6, s48, 1
	s_or_b32 s6, s6, 1
	s_mul_hi_i32 s10, s6, 0x4400
	s_mul_i32 s11, s6, 0x4400
	v_readlane_b32 s6, v254, 16
	s_nop 0
	s_add_u32 s31, s6, s4
	v_readlane_b32 s4, v254, 17
	s_addc_u32 s46, s4, s5
	v_readlane_b32 s4, v253, 43
	s_mov_b32 s51, s4
	s_waitcnt lgkmcnt(0)
	s_nop 0
	v_readlane_b32 s5, v253, 44
	s_mov_b32 s100, 1
	s_branch .LBB0_104

; #define WAIT_V0() asm volatile("s_waitcnt vmcnt(0)" ::: "memory")
; #define G_LANE_SETUP() \
;     int tid_ = threadIdx.x; \
;     asm volatile("" : "+v"(tid_));    \
;     const int wid = tid_ >> 6, lane = tid_ & 63, wr = wid >> 2, wc = wid & 3, fr = lane & 15, fq = lane >> 4; \
;     unsigned soff[4];        \
;     _Pragma("unroll") for (int i = 0; i < 4; ++i) { int sR, sC; stage_rc2(wid * 1024 + i * 8192 + lane * 16, sR, sC); soff[i] = (unsigned)(sR * K + sC) * 2u; }
; #define G_RDA(AF, buf, ks, mh) do { _Pragma("unroll") for (int m = 0; m < 4; ++m) AF[m] = *(const LDSP bf16x8*)(G_SA(buf) + aoff + ((mh) * 4 + m) * 2048 + (ks) * 1024); } while (0)
; #define G_SB0() __builtin_amdgcn_sched_barrier(0)
; template <int EK>
; DI void gemm_stream(const Params& p, int l, const bf16_t* __restrict__ A, const bf16_t* __restrict__ Bt, int M, int N, int K, ldsp_t shm) {
;     ...
;     const int nt = K / 64;
;     int pm, pn;
;     tile_coords(L, nM, nN, pm, pn);
;     const bf16_t* Ab = A + (size_t)pm * 256 * K;
;     const bf16_t* Bb = Bt + (size_t)pn * 256 * K;
;     { G_LANE_SETUP(); (void)wr; (void)wc; (void)fr; (void)fq; G_STAGE(Ab, Bb, 0, 0); WAIT_V0(); __syncthreads(); }
;     while (true) {
;         G_LANE_SETUP();
;         const int aoff = lds_byte2(wr * 128 + fr, fq * 8), boff = lds_byte2(wc * 64 + fr, fq * 8);
;         f32x4 acc[8][4];
; #pragma unroll
;         for (int m = 0; m < 8; ++m)
; #pragma unroll
;             for (int n = 0; n < 4; ++n) acc[m][n] = (f32x4){0.f, 0.f, 0.f, 0.f};
;         const int Ln = L + gridDim.x;
;         const bool has_next = Ln < nwg;
;         int pm2 = pm, pn2 = pn;
;         if (has_next) tile_coords(Ln, nM, nN, pm2, pn2);
;         const bf16_t* Ab2 = A + (size_t)pm2 * 256 * K;
;         const bf16_t* Bb2 = Bt + (size_t)pn2 * 256 * K;
;         bf16x8 Aa[4], Ab_[4], Bk0[4], Bk1[4];
;     ...
;         for (int t = 0; t < nt; ++t) {
;             const int cur = t & 1;
;             G_RDA(Aa, cur, 0, 0); G_RDB(Bk0, cur, 0);
;             if (t + 1 < nt) G_STAGE_B(Bb, cur ^ 1, t + 1);
;             else if (has_next) G_STAGE_B(Bb2, cur ^ 1, 0);
;             G_SB0();
;             if (t > 0) G_MMA(Ab_, Bk1, 1);
;             G_SB0();
;             if (t + 1 < nt) G_STAGE_A(Ab, cur ^ 1, t + 1);
;             else if (has_next) G_STAGE_A(Ab2, cur ^ 1, 0);
;             G_RDA(Ab_, cur, 0, 1);
.LBB0_110:
	v_lshlrev_b32_e32 v0, 4, v160
	v_and_b32_e32 v1, 32, v160
	v_bfe_u32 v161, v160, 2, 4
	v_and_b32_e32 v190, 64, v160
	v_bitop3_b32 v191, v0, v1, 48 bitop3:0x6c
	v_lshrrev_b32_e32 v2, 3, v160
	v_or_b32_e32 v1, v191, v190
	v_and_or_b32 v2, v2, s86, v161
	v_add_u32_e32 v200, 0x2000, v0
	v_lshl_or_b32 v192, v2, 11, v1
	v_lshrrev_b32_e32 v2, 7, v200
	v_and_or_b32 v2, v2, s86, v161
	v_add_u32_e32 v201, 0x4000, v0
	v_add_u32_e32 v221, 0x6000, v0
	v_and_b32_e32 v220, 0xfffffc00, v0
	v_lshl_or_b32 v194, v2, 11, v1
	v_lshrrev_b32_e32 v2, 7, v201
	v_lshrrev_b32_e32 v0, 7, v221
	v_and_or_b32 v2, v2, s86, v161
	v_and_or_b32 v0, v0, s86, v161
	v_lshl_or_b32 v196, v2, 11, v1
	v_lshl_or_b32 v198, v0, 11, v1
	v_lshlrev_b32_e32 v1, 6, v160
	v_lshlrev_b32_e32 v4, 2, v160
	v_and_b32_e32 v0, 48, v160
	v_and_b32_e32 v2, 0x3c0, v1
	v_and_b32_e32 v4, 32, v4
	v_bitop3_b32 v0, v2, v4, v0 bitop3:0x36
	s_movk_i32 s4, 0xc000
	v_and_or_b32 v218, v1, s4, v0
	s_add_u32 s4, s9, s38
	s_addc_u32 s5, s45, s39
	v_add_u32_e32 v34, 0x18000, v220
	v_lshl_add_u64 v[32:33], s[4:5], 0, v[192:193]
	v_readfirstlane_b32 s35, v34
	v_lshlrev_b32_e32 v3, 7, v160
	v_lshl_add_u64 v[32:33], v[32:33], 0, s[0:1]
	s_mov_b32 m0, s35
	v_mov_b32_e32 v195, v193
	v_add_u32_e32 v34, 0x1a000, v220
	v_and_or_b32 v219, v3, s28, v0
	global_load_lds_dwordx4 v[32:33], off
	v_lshl_add_u64 v[32:33], s[4:5], 0, v[194:195]
	v_readfirstlane_b32 s35, v34
	v_lshl_add_u64 v[32:33], v[32:33], 0, s[0:1]
	s_mov_b32 m0, s35
	v_mov_b32_e32 v197, v193
	v_add_u32_e32 v34, 0x1c000, v220
	global_load_lds_dwordx4 v[32:33], off
	v_lshl_add_u64 v[32:33], s[4:5], 0, v[196:197]
	v_readfirstlane_b32 s35, v34
	v_lshl_add_u64 v[32:33], v[32:33], 0, s[0:1]
	s_mov_b32 m0, s35
	v_mov_b32_e32 v199, v193
	v_add_u32_e32 v34, 0x1e000, v220
	global_load_lds_dwordx4 v[32:33], off
	v_lshl_add_u64 v[32:33], s[4:5], 0, v[198:199]
	v_readfirstlane_b32 s4, v34
	v_lshl_add_u64 v[32:33], v[32:33], 0, s[0:1]
	s_mov_b32 m0, s4
	s_nop 0
	global_load_lds_dwordx4 v[32:33], off
	s_add_u32 s4, s82, s40
	s_addc_u32 s5, s83, s41
	v_add_u32_e32 v34, 0x10000, v220
	v_lshl_add_u64 v[32:33], s[4:5], 0, v[192:193]
	v_readfirstlane_b32 s35, v34
	v_lshl_add_u64 v[32:33], v[32:33], 0, s[0:1]
	s_mov_b32 m0, s35
	v_add_u32_e32 v34, 0x12000, v220
	global_load_lds_dwordx4 v[32:33], off
	v_lshl_add_u64 v[32:33], s[4:5], 0, v[194:195]
	v_readfirstlane_b32 s35, v34
	v_lshl_add_u64 v[32:33], v[32:33], 0, s[0:1]
	s_mov_b32 m0, s35
	v_add_u32_e32 v34, 0x14000, v220
	global_load_lds_dwordx4 v[32:33], off
	v_lshl_add_u64 v[32:33], s[4:5], 0, v[196:197]
	v_readfirstlane_b32 s35, v34
	v_lshl_add_u64 v[32:33], v[32:33], 0, s[0:1]
	s_mov_b32 m0, s35
	v_add_u32_e32 v34, 0x16000, v220
	global_load_lds_dwordx4 v[32:33], off
	v_lshl_add_u64 v[32:33], s[4:5], 0, v[198:199]
	v_readfirstlane_b32 s4, v34
	v_lshl_add_u64 v[32:33], v[32:33], 0, s[0:1]
	s_mov_b32 m0, s4
	s_mov_b32 s35, 0x10000
	global_load_lds_dwordx4 v[32:33], off
	s_cmp_eq_u32 s100, 1
	s_cbranch_scc0 .Lpro2_skip0
	s_waitcnt vmcnt(8)
; #define WAIT_V0() asm volatile("s_waitcnt vmcnt(0)" ::: "memory")
; #define G_STAGE_A(Ap, buf, kt) do { const char* ab_ = (const char*)(Ap) + (size_t)(kt) * 128; \
;       _Pragma("unroll") for (int i = 0; i < 4; ++i) \
;         __builtin_amdgcn_global_load_lds((const unsigned*)(ab_ + soff[i]), (LDSP unsigned*)(G_SA(buf) + wid * 1024 + i * 8192), 16, 0, 0); } while (0)
; #define G_STAGE_B(Bp, buf, kt) do { const char* bb_ = (const char*)(Bp) + (size_t)(kt) * 128; \
;       _Pragma("unroll") for (int i = 0; i < 4; ++i) \
;         __builtin_amdgcn_global_load_lds((const unsigned*)(bb_ + soff[i]), (LDSP unsigned*)(G_SB(buf) + wid * 1024 + i * 8192), 16, 0, 0); } while (0)
; #define G_RDA(AF, buf, ks, mh) do { _Pragma("unroll") for (int m = 0; m < 4; ++m) AF[m] = *(const LDSP bf16x8*)(G_SA(buf) + aoff + ((mh) * 4 + m) * 2048 + (ks) * 1024); } while (0)
; #define G_RDB(BF, buf, ks) do { _Pragma("unroll") for (int n = 0; n < 4; ++n) BF[n] = *(const LDSP bf16x8*)(G_SB(buf) + boff + n * 2048 + (ks) * 1024); } while (0)
; #define G_SB0() __builtin_amdgcn_sched_barrier(0)
; template <int EK>
; DI void gemm_stream(const Params& p, int l, const bf16_t* __restrict__ A, const bf16_t* __restrict__ Bt, int M, int N, int K, ldsp_t shm) {
;     ...
;         bf16x8 Aa[4], Ab_[4], Bk0[4], Bk1[4];
;     ...
;         for (int t = 0; t < nt; ++t) {
;             const int cur = t & 1;
;             G_RDA(Aa, cur, 0, 0); G_RDB(Bk0, cur, 0);
;             if (t + 1 < nt) G_STAGE_B(Bb, cur ^ 1, t + 1);
;             else if (has_next) G_STAGE_B(Bb2, cur ^ 1, 0);
;             G_SB0();
;             if (t > 0) G_MMA(Ab_, Bk1, 1);
;             G_SB0();
;             if (t + 1 < nt) G_STAGE_A(Ab, cur ^ 1, t + 1);
;             else if (has_next) G_STAGE_A(Ab2, cur ^ 1, 0);
;             G_RDA(Ab_, cur, 0, 1);
;             G_MMA(Aa, Bk0, 0); G_SB0();
;             G_RDA(Aa, cur, 1, 0); G_RDB(Bk1, cur, 1);
;             G_MMA(Ab_, Bk0, 1); G_SB0();
;             G_RDA(Ab_, cur, 1, 1);
;             G_MMA(Aa, Bk1, 0); G_SB0();
;             asm volatile("s_waitcnt lgkmcnt(0)" ::: "memory");
;             WAIT_V0(); __syncthreads();
;         }
;         G_MMA(Ab_, Bk1, 1);
.Lpro2_skip0:
	s_mov_b32 s100, 0
	s_barrier
	ds_read_b128 v[0:3], v218
	ds_read_b128 v[4:7], v218 offset:2048
	ds_read_b128 v[8:11], v218 offset:4096
	ds_read_b128 v[12:15], v218 offset:6144
	ds_read_b128 v[16:19], v219 offset:32768
	ds_read_b128 v[20:23], v219 offset:34816
	ds_read_b128 v[24:27], v219 offset:36864
	ds_read_b128 v[28:31], v219 offset:38912
	ds_read_b128 v[32:35], v218 offset:8192
	ds_read_b128 v[36:39], v218 offset:10240
	ds_read_b128 v[40:43], v218 offset:12288
	ds_read_b128 v[44:47], v218 offset:14336
	s_setprio 1
	s_waitcnt lgkmcnt(0)
	v_mfma_f32_16x16x32_bf16 v[48:51], v[16:19], v[0:3], 0
	v_mfma_f32_16x16x32_bf16 v[52:55], v[20:23], v[0:3], 0
	v_mfma_f32_16x16x32_bf16 v[162:165], v[24:27], v[0:3], 0
	v_mfma_f32_16x16x32_bf16 v[0:3], v[28:31], v[0:3], 0
	v_mfma_f32_16x16x32_bf16 v[166:169], v[16:19], v[4:7], 0
	v_mfma_f32_16x16x32_bf16 v[170:173], v[20:23], v[4:7], 0
	v_mfma_f32_16x16x32_bf16 v[174:177], v[24:27], v[4:7], 0
	v_mfma_f32_16x16x32_bf16 v[4:7], v[28:31], v[4:7], 0
	v_mfma_f32_16x16x32_bf16 v[178:181], v[16:19], v[8:11], 0
	v_mfma_f32_16x16x32_bf16 v[182:185], v[20:23], v[8:11], 0
	v_mfma_f32_16x16x32_bf16 v[186:189], v[24:27], v[8:11], 0
	v_mfma_f32_16x16x32_bf16 v[8:11], v[28:31], v[8:11], 0
	v_mfma_f32_16x16x32_bf16 v[204:207], v[16:19], v[12:15], 0
	v_mfma_f32_16x16x32_bf16 v[210:213], v[20:23], v[12:15], 0
	v_mfma_f32_16x16x32_bf16 v[214:217], v[24:27], v[12:15], 0
	v_mfma_f32_16x16x32_bf16 v[222:225], v[28:31], v[12:15], 0
	s_setprio 0
	ds_read_b128 v[12:15], v218 offset:1024
	ds_read_b128 v[226:229], v218 offset:3072
	ds_read_b128 v[230:233], v218 offset:5120
	ds_read_b128 v[234:237], v218 offset:7168
	ds_read_b128 v[64:67], v219 offset:33792
	ds_read_b128 v[68:71], v219 offset:35840
	ds_read_b128 v[76:79], v219 offset:37888
	ds_read_b128 v[72:75], v219 offset:39936
	s_setprio 1
	v_mfma_f32_16x16x32_bf16 v[128:131], v[16:19], v[32:35], 0
	v_mfma_f32_16x16x32_bf16 v[124:127], v[20:23], v[32:35], 0
	v_mfma_f32_16x16x32_bf16 v[120:123], v[24:27], v[32:35], 0
	v_mfma_f32_16x16x32_bf16 v[116:119], v[28:31], v[32:35], 0
	v_mfma_f32_16x16x32_bf16 v[112:115], v[16:19], v[36:39], 0
	v_mfma_f32_16x16x32_bf16 v[108:111], v[20:23], v[36:39], 0
	v_mfma_f32_16x16x32_bf16 v[104:107], v[24:27], v[36:39], 0
	v_mfma_f32_16x16x32_bf16 v[100:103], v[28:31], v[36:39], 0
	v_mfma_f32_16x16x32_bf16 v[96:99], v[16:19], v[40:43], 0
	v_mfma_f32_16x16x32_bf16 v[92:95], v[20:23], v[40:43], 0
	v_mfma_f32_16x16x32_bf16 v[88:91], v[24:27], v[40:43], 0
	v_mfma_f32_16x16x32_bf16 v[84:87], v[28:31], v[40:43], 0
	v_mfma_f32_16x16x32_bf16 v[132:135], v[16:19], v[44:47], 0
	v_mfma_f32_16x16x32_bf16 v[136:139], v[20:23], v[44:47], 0
	v_mfma_f32_16x16x32_bf16 v[140:143], v[24:27], v[44:47], 0
	v_mfma_f32_16x16x32_bf16 v[80:83], v[28:31], v[44:47], 0
	s_setprio 0
	ds_read_b128 v[156:159], v218 offset:9216
	ds_read_b128 v[152:155], v218 offset:11264
	ds_read_b128 v[148:151], v218 offset:13312
	ds_read_b128 v[144:147], v218 offset:15360
	s_setprio 1
	s_waitcnt lgkmcnt(0)
	v_mfma_f32_16x16x32_bf16 v[60:63], v[64:67], v[12:15], v[48:51]
	v_mfma_f32_16x16x32_bf16 v[56:59], v[68:71], v[12:15], v[52:55]
	v_mfma_f32_16x16x32_bf16 v[52:55], v[76:79], v[12:15], v[162:165]
	v_mfma_f32_16x16x32_bf16 v[48:51], v[72:75], v[12:15], v[0:3]
	v_mfma_f32_16x16x32_bf16 v[44:47], v[64:67], v[226:229], v[166:169]
	v_mfma_f32_16x16x32_bf16 v[40:43], v[68:71], v[226:229], v[170:173]
	v_mfma_f32_16x16x32_bf16 v[36:39], v[76:79], v[226:229], v[174:177]
	v_mfma_f32_16x16x32_bf16 v[32:35], v[72:75], v[226:229], v[4:7]
	v_mfma_f32_16x16x32_bf16 v[28:31], v[64:67], v[230:233], v[178:181]
	v_mfma_f32_16x16x32_bf16 v[24:27], v[68:71], v[230:233], v[182:185]
	v_mfma_f32_16x16x32_bf16 v[20:23], v[76:79], v[230:233], v[186:189]
	v_mfma_f32_16x16x32_bf16 v[16:19], v[72:75], v[230:233], v[8:11]
	v_mfma_f32_16x16x32_bf16 v[12:15], v[64:67], v[234:237], v[204:207]
	v_mfma_f32_16x16x32_bf16 v[8:11], v[68:71], v[234:237], v[210:213]
	v_mfma_f32_16x16x32_bf16 v[4:7], v[76:79], v[234:237], v[214:217]
	v_mfma_f32_16x16x32_bf16 v[0:3], v[72:75], v[234:237], v[222:225]
	s_setprio 0
	v_lshlrev_b32_e32 v160, 8, v160
	v_lshlrev_b32_e32 v162, 4, v200
	v_lshlrev_b32_e32 v164, 4, v201
	v_lshlrev_b32_e32 v167, 4, v221
	v_and_or_b32 v160, v160, s90, v191
	v_lshlrev_b32_e32 v166, 11, v161
	s_add_u32 s4, s31, s38
	v_and_or_b32 v162, v162, s90, v191
	v_and_or_b32 v164, v164, s90, v191
	v_and_or_b32 v167, v167, s90, v191
	v_or3_b32 v168, v160, v166, v190
	v_mov_b32_e32 v169, v193
	s_addc_u32 s5, s46, s39
	v_or3_b32 v170, v162, v166, v190
	v_mov_b32_e32 v171, v193
	v_or3_b32 v172, v164, v166, v190
	v_mov_b32_e32 v173, v193
	v_or3_b32 v174, v167, v166, v190
	v_mov_b32_e32 v175, v193
	s_waitcnt lgkmcnt(0)
	v_writelane_b32 v255, s52, 12
	v_writelane_b32 v255, s53, 13
	v_writelane_b32 v255, s64, 14
	v_writelane_b32 v255, s65, 15
	v_writelane_b32 v255, s30, 16
	s_mov_b64 s[64:65], s[4:5]
	v_readlane_b32 s4, v254, 18
	s_waitcnt vmcnt(0)
	s_add_u32 s4, s4, s40
	v_readlane_b32 s5, v254, 19
	s_addc_u32 s5, s5, s41
	s_waitcnt vmcnt(0)
	s_mov_b64 s[52:53], s[4:5]
	s_mov_b64 s[4:5], 0
	v_lshrrev_b32_e32 v164, 6, v252
	v_lshlrev_b32_e32 v164, 10, v164
	s_nop 0
	v_readfirstlane_b32 s30, v164
	v_and_b32_e32 v165, 63, v252
	v_lshlrev_b32_e32 v165, 4, v165
	s_barrier
	s_and_b32 s37, s35, 0x10000
	v_add_u32_e32 v221, s37, v218
	v_or_b32_e32 v226, s37, v219
	s_xor_b32 s37, s37, 0x10000
	s_add_u32 s37, s37, s30
	.p2align	6

; #define WAIT_V0() asm volatile("s_waitcnt vmcnt(0)" ::: "memory")
; #define G_LANE_SETUP() \
;     int tid_ = threadIdx.x; \
;     asm volatile("" : "+v"(tid_));    \
;     const int wid = tid_ >> 6, lane = tid_ & 63, wr = wid >> 2, wc = wid & 3, fr = lane & 15, fq = lane >> 4; \
;     unsigned soff[4];        \
;     _Pragma("unroll") for (int i = 0; i < 4; ++i) { int sR, sC; stage_rc2(wid * 1024 + i * 8192 + lane * 16, sR, sC); soff[i] = (unsigned)(sR * K + sC) * 2u; }
; template <int EK>
; DI void gemm_stream(const Params& p, int l, const bf16_t* __restrict__ A, const bf16_t* __restrict__ Bt, int M, int N, int K, ldsp_t shm) {
;     ...
;     const int nt = K / 64;
;     int pm, pn;
;     tile_coords(L, nM, nN, pm, pn);
;     const bf16_t* Ab = A + (size_t)pm * 256 * K;
;     const bf16_t* Bb = Bt + (size_t)pn * 256 * K;
;     { G_LANE_SETUP(); (void)wr; (void)wc; (void)fr; (void)fq; G_STAGE(Ab, Bb, 0, 0); WAIT_V0(); __syncthreads(); }
; DI void run_phase(const Params& p, int ph, ldsp_t smem) {
;     ...
;     const int l = (ph - 2) / 5, k = (ph - 2) % 5;
;     const bool last = l == DEPTH - 1;
;     switch (k) {
;         case 0: gemm_stream<0>(p, l, p.H, p.wt_in + (size_t)l * IN_DIM * DM, NTOK, IN_DIM, DM, smem); break;
.LBB0_251:
	s_movk_i32 s85, 0x70
	s_movk_i32 s84, 0x80
	s_and_b64 vcc, exec, s[4:5]
	s_cbranch_vccz .LBB0_370
	v_readlane_b32 s4, v253, 36
	v_readlane_b32 s5, v253, 37
	s_andn2_b64 vcc, exec, s[4:5]
	s_cbranch_vccnz .LBB0_370
	v_mov_b32_e32 v0, v252
	s_mul_i32 s7, s48, 0x380000
	v_lshlrev_b32_e32 v1, 4, v0
	v_and_b32_e32 v3, 32, v0
	v_and_b32_e32 v2, 0xfffffc00, v1
	v_bitop3_b32 v3, v1, v3, 48 bitop3:0x6c
	s_waitcnt lgkmcnt(0)
	v_add_u32_e32 v5, 0x2000, v1
	v_add_u32_e32 v6, 0x4000, v1
	v_add_u32_e32 v1, 0x6000, v1
	v_bfe_u32 v4, v0, 2, 4
	v_and_or_b32 v3, v0, 64, v3
	v_lshrrev_b32_e32 v0, 3, v0
	v_lshrrev_b32_e32 v5, 7, v5
	v_lshrrev_b32_e32 v6, 7, v6
	v_lshrrev_b32_e32 v1, 7, v1
	s_mul_hi_i32 s6, s48, 0x380000
	s_add_u32 s14, s56, s7
	v_and_or_b32 v0, v0, s86, v4
	v_and_or_b32 v5, v5, s86, v4
	v_and_or_b32 v6, v6, s86, v4
	v_and_or_b32 v1, v1, s86, v4
	s_addc_u32 s15, s57, s6
	v_lshl_or_b32 v0, v0, 11, v3
	v_lshl_or_b32 v5, v5, 11, v3
	v_lshl_or_b32 v6, v6, 11, v3
	v_lshl_or_b32 v1, v1, 11, v3
	v_readlane_b32 s10, v254, 10
	v_add_u32_e32 v3, 0x8000, v2
	v_readfirstlane_b32 s9, v2
	v_readlane_b32 s12, v254, 14
	v_readlane_b32 s11, v254, 11
	s_add_u32 s4, s14, s10
	s_mov_b32 m0, s9
	v_readlane_b32 s13, v254, 15
	v_readfirstlane_b32 s9, v3
	s_addc_u32 s5, s15, s11
	s_mul_i32 s8, s48, 0x8800
	v_readlane_b32 s98, v254, 7
	v_readlane_b32 s93, v253, 0
	global_load_lds_dwordx4 v0, s[12:13]
	s_mov_b32 m0, s9
	s_nop 0
	global_load_lds_dwordx4 v0, s[4:5]
	v_add_u32_e32 v0, 0x2000, v2
	s_nop 0
	v_readfirstlane_b32 s9, v0
	v_add_u32_e32 v0, 0xa000, v2
	s_mov_b32 m0, s9
	v_readfirstlane_b32 s9, v0
	v_add_u32_e32 v0, 0x4000, v2
	global_load_lds_dwordx4 v5, s[12:13]
	s_mov_b32 m0, s9
	v_readfirstlane_b32 s9, v0
	v_add_u32_e32 v0, 0xc000, v2
	global_load_lds_dwordx4 v5, s[4:5]
	s_mov_b32 m0, s9
	v_readfirstlane_b32 s9, v0
	v_add_u32_e32 v0, 0x6000, v2
	global_load_lds_dwordx4 v6, s[12:13]
	s_mov_b32 m0, s9
	v_readfirstlane_b32 s9, v0
	v_add_u32_e32 v0, 0xe000, v2
	global_load_lds_dwordx4 v6, s[4:5]
	s_mov_b32 m0, s9
	v_readfirstlane_b32 s9, v0
	global_load_lds_dwordx4 v1, s[12:13]
	s_mov_b32 m0, s9
	s_mul_hi_i32 s12, s48, 5
	global_load_lds_dwordx4 v1, s[4:5]
	s_lshl_b32 s4, s48, 1
	s_mul_hi_i32 s9, s4, 0x4400
	s_lshl_b32 s4, s48, 6
	s_ashr_i32 s5, s4, 31
	v_readlane_b32 s36, v253, 3
	s_lshl_b64 s[4:5], s[4:5], 2
	v_readlane_b32 s38, v253, 5
	v_readlane_b32 s45, v253, 12
	v_readlane_b32 s39, v253, 6
	v_readlane_b32 s48, v253, 15
	s_mov_b32 s45, s8
	s_add_u32 s8, s38, s4
	v_readlane_b32 s49, v253, 16
	s_mov_b32 s48, s9
	s_addc_u32 s9, s39, s5
	v_readlane_b32 s37, v253, 4
	s_mov_b32 s49, s12
	s_add_u32 s12, s36, s4
	v_writelane_b32 v255, s8, 5
	s_addc_u32 s13, s37, s5
	v_readlane_b32 s4, v254, 38
	v_writelane_b32 v255, s9, 6
	s_add_u32 s4, s4, s7
	v_writelane_b32 v255, s4, 10
	v_readlane_b32 s4, v254, 39
	s_nop 0
	s_addc_u32 s4, s4, s6
	v_readlane_b32 s44, v253, 11
	v_readlane_b32 s46, v253, 13
	v_readlane_b32 s47, v253, 14
	v_writelane_b32 v255, s4, 7
	v_readlane_b32 s4, v254, 8
	v_readlane_b32 s36, v254, 12
	s_mov_b32 s31, s4
	s_mov_b64 s[46:47], s[10:11]
	v_readlane_b32 s37, v254, 13
	v_readlane_b32 s38, v254, 18
	v_readlane_b32 s39, v254, 19
	v_readlane_b32 s44, v255, 4
	s_waitcnt lgkmcnt(0)
	s_nop 0
	v_readlane_b32 s40, v253, 7
	v_readlane_b32 s41, v253, 8
	v_readlane_b32 s42, v253, 9
	v_readlane_b32 s43, v253, 10
	v_readlane_b32 s50, v253, 17
	v_readlane_b32 s51, v253, 18
	v_readlane_b32 s5, v254, 9
	s_mov_b32 s100, 1
	s_branch .LBB0_257

; #define WAIT_V0() asm volatile("s_waitcnt vmcnt(0)" ::: "memory")
; #define G_LANE_SETUP() \
;     int tid_ = threadIdx.x; \
;     asm volatile("" : "+v"(tid_));    \
;     const int wid = tid_ >> 6, lane = tid_ & 63, wr = wid >> 2, wc = wid & 3, fr = lane & 15, fq = lane >> 4; \
;     unsigned soff[4];        \
;     _Pragma("unroll") for (int i = 0; i < 4; ++i) { int sR, sC; stage_rc2(wid * 1024 + i * 8192 + lane * 16, sR, sC); soff[i] = (unsigned)(sR * K + sC) * 2u; }
; #define G_RDA(AF, buf, ks, mh) do { _Pragma("unroll") for (int m = 0; m < 4; ++m) AF[m] = *(const LDSP bf16x8*)(G_SA(buf) + aoff + ((mh) * 4 + m) * 2048 + (ks) * 1024); } while (0)
; #define G_SB0() __builtin_amdgcn_sched_barrier(0)
; template <int EK>
; DI void gemm_stream(const Params& p, int l, const bf16_t* __restrict__ A, const bf16_t* __restrict__ Bt, int M, int N, int K, ldsp_t shm) {
;     ...
;     const int nt = K / 64;
;     int pm, pn;
;     tile_coords(L, nM, nN, pm, pn);
;     const bf16_t* Ab = A + (size_t)pm * 256 * K;
;     const bf16_t* Bb = Bt + (size_t)pn * 256 * K;
;     { G_LANE_SETUP(); (void)wr; (void)wc; (void)fr; (void)fq; G_STAGE(Ab, Bb, 0, 0); WAIT_V0(); __syncthreads(); }
;     while (true) {
;         G_LANE_SETUP();
;         const int aoff = lds_byte2(wr * 128 + fr, fq * 8), boff = lds_byte2(wc * 64 + fr, fq * 8);
;         f32x4 acc[8][4];
; #pragma unroll
;         for (int m = 0; m < 8; ++m)
; #pragma unroll
;             for (int n = 0; n < 4; ++n) acc[m][n] = (f32x4){0.f, 0.f, 0.f, 0.f};
;         const int Ln = L + gridDim.x;
;         const bool has_next = Ln < nwg;
;         int pm2 = pm, pn2 = pn;
;         if (has_next) tile_coords(Ln, nM, nN, pm2, pn2);
;         const bf16_t* Ab2 = A + (size_t)pm2 * 256 * K;
;         const bf16_t* Bb2 = Bt + (size_t)pn2 * 256 * K;
;         bf16x8 Aa[4], Ab_[4], Bk0[4], Bk1[4];
;     ...
;         for (int t = 0; t < nt; ++t) {
;             const int cur = t & 1;
;             G_RDA(Aa, cur, 0, 0); G_RDB(Bk0, cur, 0);
;             if (t + 1 < nt) G_STAGE_B(Bb, cur ^ 1, t + 1);
;             else if (has_next) G_STAGE_B(Bb2, cur ^ 1, 0);
;             G_SB0();
;             if (t > 0) G_MMA(Ab_, Bk1, 1);
;             G_SB0();
;             if (t + 1 < nt) G_STAGE_A(Ab, cur ^ 1, t + 1);
;             else if (has_next) G_STAGE_A(Ab2, cur ^ 1, 0);
;             G_RDA(Ab_, cur, 0, 1);
.LBB0_263:
	v_lshlrev_b32_e32 v0, 4, v160
	v_and_b32_e32 v1, 32, v160
	v_bfe_u32 v161, v160, 2, 4
	v_and_b32_e32 v190, 64, v160
	v_bitop3_b32 v191, v0, v1, 48 bitop3:0x6c
	v_lshrrev_b32_e32 v2, 3, v160
	v_or_b32_e32 v1, v191, v190
	v_and_or_b32 v2, v2, s86, v161
	v_add_u32_e32 v200, 0x2000, v0
	v_lshl_or_b32 v192, v2, 11, v1
	v_lshrrev_b32_e32 v2, 7, v200
	v_and_or_b32 v2, v2, s86, v161
	v_add_u32_e32 v201, 0x4000, v0
	v_add_u32_e32 v204, 0x6000, v0
	v_and_b32_e32 v220, 0xfffffc00, v0
	v_lshl_or_b32 v194, v2, 11, v1
	v_lshrrev_b32_e32 v2, 7, v201
	v_lshrrev_b32_e32 v0, 7, v204
	v_and_or_b32 v2, v2, s86, v161
	v_and_or_b32 v0, v0, s86, v161
	v_lshl_or_b32 v196, v2, 11, v1
	v_lshl_or_b32 v198, v0, 11, v1
	v_lshlrev_b32_e32 v1, 6, v160
	v_lshlrev_b32_e32 v4, 2, v160
	v_and_b32_e32 v0, 48, v160
	v_and_b32_e32 v2, 0x3c0, v1
	v_and_b32_e32 v4, 32, v4
	v_bitop3_b32 v0, v2, v4, v0 bitop3:0x36
	s_movk_i32 s4, 0xc000
	v_and_or_b32 v218, v1, s4, v0
	s_add_u32 s4, s14, s46
	s_addc_u32 s5, s15, s47
	v_add_u32_e32 v34, 0x18000, v220
	v_lshl_add_u64 v[32:33], s[4:5], 0, v[192:193]
	v_readfirstlane_b32 s8, v34
	v_lshlrev_b32_e32 v3, 7, v160
	v_lshl_add_u64 v[32:33], v[32:33], 0, s[0:1]
	s_mov_b32 m0, s8
	v_mov_b32_e32 v195, v193
	v_add_u32_e32 v34, 0x1a000, v220
	v_and_or_b32 v219, v3, s28, v0
	global_load_lds_dwordx4 v[32:33], off
	v_lshl_add_u64 v[32:33], s[4:5], 0, v[194:195]
	v_readfirstlane_b32 s8, v34
	v_lshl_add_u64 v[32:33], v[32:33], 0, s[0:1]
	s_mov_b32 m0, s8
	v_mov_b32_e32 v197, v193
	v_add_u32_e32 v34, 0x1c000, v220
	global_load_lds_dwordx4 v[32:33], off
	v_lshl_add_u64 v[32:33], s[4:5], 0, v[196:197]
	v_readfirstlane_b32 s8, v34
	v_lshl_add_u64 v[32:33], v[32:33], 0, s[0:1]
	s_mov_b32 m0, s8
	v_mov_b32_e32 v199, v193
	v_add_u32_e32 v34, 0x1e000, v220
	global_load_lds_dwordx4 v[32:33], off
	v_lshl_add_u64 v[32:33], s[4:5], 0, v[198:199]
	v_readfirstlane_b32 s4, v34
	v_lshl_add_u64 v[32:33], v[32:33], 0, s[0:1]
	s_mov_b32 m0, s4
	s_nop 0
	global_load_lds_dwordx4 v[32:33], off
	s_add_u32 s4, s82, s36
	s_addc_u32 s5, s83, s37
	v_add_u32_e32 v34, 0x10000, v220
	v_lshl_add_u64 v[32:33], s[4:5], 0, v[192:193]
	v_readfirstlane_b32 s8, v34
	v_lshl_add_u64 v[32:33], v[32:33], 0, s[0:1]
	s_mov_b32 m0, s8
	v_add_u32_e32 v34, 0x12000, v220
	global_load_lds_dwordx4 v[32:33], off
	v_lshl_add_u64 v[32:33], s[4:5], 0, v[194:195]
	v_readfirstlane_b32 s8, v34
	v_lshl_add_u64 v[32:33], v[32:33], 0, s[0:1]
	s_mov_b32 m0, s8
	v_add_u32_e32 v34, 0x14000, v220
	global_load_lds_dwordx4 v[32:33], off
	v_lshl_add_u64 v[32:33], s[4:5], 0, v[196:197]
	v_readfirstlane_b32 s8, v34
	v_lshl_add_u64 v[32:33], v[32:33], 0, s[0:1]
	s_mov_b32 m0, s8
	v_add_u32_e32 v34, 0x16000, v220
	global_load_lds_dwordx4 v[32:33], off
	v_lshl_add_u64 v[32:33], s[4:5], 0, v[198:199]
	v_readfirstlane_b32 s4, v34
	v_lshl_add_u64 v[32:33], v[32:33], 0, s[0:1]
	s_mov_b32 m0, s4
	s_mov_b32 s8, 0x10000
	global_load_lds_dwordx4 v[32:33], off
	s_cmp_eq_u32 s100, 1
	s_cbranch_scc0 .Lpro2_skip1
	s_waitcnt vmcnt(8)
; #define WAIT_V0() asm volatile("s_waitcnt vmcnt(0)" ::: "memory")
; #define G_STAGE_A(Ap, buf, kt) do { const char* ab_ = (const char*)(Ap) + (size_t)(kt) * 128; \
;       _Pragma("unroll") for (int i = 0; i < 4; ++i) \
;         __builtin_amdgcn_global_load_lds((const unsigned*)(ab_ + soff[i]), (LDSP unsigned*)(G_SA(buf) + wid * 1024 + i * 8192), 16, 0, 0); } while (0)
; #define G_STAGE_B(Bp, buf, kt) do { const char* bb_ = (const char*)(Bp) + (size_t)(kt) * 128; \
;       _Pragma("unroll") for (int i = 0; i < 4; ++i) \
;         __builtin_amdgcn_global_load_lds((const unsigned*)(bb_ + soff[i]), (LDSP unsigned*)(G_SB(buf) + wid * 1024 + i * 8192), 16, 0, 0); } while (0)
; #define G_RDA(AF, buf, ks, mh) do { _Pragma("unroll") for (int m = 0; m < 4; ++m) AF[m] = *(const LDSP bf16x8*)(G_SA(buf) + aoff + ((mh) * 4 + m) * 2048 + (ks) * 1024); } while (0)
; #define G_RDB(BF, buf, ks) do { _Pragma("unroll") for (int n = 0; n < 4; ++n) BF[n] = *(const LDSP bf16x8*)(G_SB(buf) + boff + n * 2048 + (ks) * 1024); } while (0)
; #define G_SB0() __builtin_amdgcn_sched_barrier(0)
; template <int EK>
; DI void gemm_stream(const Params& p, int l, const bf16_t* __restrict__ A, const bf16_t* __restrict__ Bt, int M, int N, int K, ldsp_t shm) {
;     ...
;         bf16x8 Aa[4], Ab_[4], Bk0[4], Bk1[4];
;     ...
;         for (int t = 0; t < nt; ++t) {
;             const int cur = t & 1;
;             G_RDA(Aa, cur, 0, 0); G_RDB(Bk0, cur, 0);
;             if (t + 1 < nt) G_STAGE_B(Bb, cur ^ 1, t + 1);
;             else if (has_next) G_STAGE_B(Bb2, cur ^ 1, 0);
;             G_SB0();
;             if (t > 0) G_MMA(Ab_, Bk1, 1);
;             G_SB0();
;             if (t + 1 < nt) G_STAGE_A(Ab, cur ^ 1, t + 1);
;             else if (has_next) G_STAGE_A(Ab2, cur ^ 1, 0);
;             G_RDA(Ab_, cur, 0, 1);
;             G_MMA(Aa, Bk0, 0); G_SB0();
;             G_RDA(Aa, cur, 1, 0); G_RDB(Bk1, cur, 1);
;             G_MMA(Ab_, Bk0, 1); G_SB0();
;             G_RDA(Ab_, cur, 1, 1);
;             G_MMA(Aa, Bk1, 0); G_SB0();
;             asm volatile("s_waitcnt lgkmcnt(0)" ::: "memory");
;             WAIT_V0(); __syncthreads();
;         }
;         G_MMA(Ab_, Bk1, 1);
.Lpro2_skip1:
	s_mov_b32 s100, 0
	s_barrier
	ds_read_b128 v[0:3], v218
	ds_read_b128 v[4:7], v218 offset:2048
	ds_read_b128 v[8:11], v218 offset:4096
	ds_read_b128 v[12:15], v218 offset:6144
	ds_read_b128 v[16:19], v219 offset:32768
	ds_read_b128 v[20:23], v219 offset:34816
	ds_read_b128 v[24:27], v219 offset:36864
	ds_read_b128 v[28:31], v219 offset:38912
	ds_read_b128 v[32:35], v218 offset:8192
	ds_read_b128 v[36:39], v218 offset:10240
	ds_read_b128 v[40:43], v218 offset:12288
	ds_read_b128 v[44:47], v218 offset:14336
	s_setprio 1
	s_waitcnt lgkmcnt(0)
	v_mfma_f32_16x16x32_bf16 v[48:51], v[16:19], v[0:3], 0
	v_mfma_f32_16x16x32_bf16 v[52:55], v[20:23], v[0:3], 0
	v_mfma_f32_16x16x32_bf16 v[56:59], v[24:27], v[0:3], 0
	v_mfma_f32_16x16x32_bf16 v[60:63], v[28:31], v[0:3], 0
	v_mfma_f32_16x16x32_bf16 v[162:165], v[16:19], v[4:7], 0
	v_mfma_f32_16x16x32_bf16 v[166:169], v[20:23], v[4:7], 0
	v_mfma_f32_16x16x32_bf16 v[170:173], v[24:27], v[4:7], 0
	v_mfma_f32_16x16x32_bf16 v[174:177], v[28:31], v[4:7], 0
	v_mfma_f32_16x16x32_bf16 v[178:181], v[16:19], v[8:11], 0
	v_mfma_f32_16x16x32_bf16 v[182:185], v[20:23], v[8:11], 0
	v_mfma_f32_16x16x32_bf16 v[186:189], v[24:27], v[8:11], 0
	v_mfma_f32_16x16x32_bf16 v[222:225], v[28:31], v[8:11], 0
	v_mfma_f32_16x16x32_bf16 v[226:229], v[16:19], v[12:15], 0
	v_mfma_f32_16x16x32_bf16 v[230:233], v[20:23], v[12:15], 0
	v_mfma_f32_16x16x32_bf16 v[234:237], v[24:27], v[12:15], 0
	v_mfma_f32_16x16x32_bf16 v[238:241], v[28:31], v[12:15], 0
	s_setprio 0
	ds_read_b128 v[12:15], v218 offset:1024
	ds_read_b128 v[242:245], v218 offset:3072
	ds_read_b128 v[246:249], v218 offset:5120
	ds_read_b128 v[214:217], v218 offset:7168
	ds_read_b128 v[64:67], v219 offset:33792
	ds_read_b128 v[68:71], v219 offset:35840
	ds_read_b128 v[76:79], v219 offset:37888
	ds_read_b128 v[72:75], v219 offset:39936
	s_setprio 1
	v_mfma_f32_16x16x32_bf16 v[128:131], v[16:19], v[32:35], 0
	v_mfma_f32_16x16x32_bf16 v[124:127], v[20:23], v[32:35], 0
	v_mfma_f32_16x16x32_bf16 v[120:123], v[24:27], v[32:35], 0
	v_mfma_f32_16x16x32_bf16 v[116:119], v[28:31], v[32:35], 0
	v_mfma_f32_16x16x32_bf16 v[112:115], v[16:19], v[36:39], 0
	v_mfma_f32_16x16x32_bf16 v[108:111], v[20:23], v[36:39], 0
	v_mfma_f32_16x16x32_bf16 v[104:107], v[24:27], v[36:39], 0
	v_mfma_f32_16x16x32_bf16 v[100:103], v[28:31], v[36:39], 0
	v_mfma_f32_16x16x32_bf16 v[96:99], v[16:19], v[40:43], 0
	v_mfma_f32_16x16x32_bf16 v[92:95], v[20:23], v[40:43], 0
	v_mfma_f32_16x16x32_bf16 v[88:91], v[24:27], v[40:43], 0
	v_mfma_f32_16x16x32_bf16 v[84:87], v[28:31], v[40:43], 0
	v_mfma_f32_16x16x32_bf16 v[132:135], v[16:19], v[44:47], 0
	v_mfma_f32_16x16x32_bf16 v[136:139], v[20:23], v[44:47], 0
	v_mfma_f32_16x16x32_bf16 v[140:143], v[24:27], v[44:47], 0
	v_mfma_f32_16x16x32_bf16 v[80:83], v[28:31], v[44:47], 0
	s_setprio 0
	ds_read_b128 v[156:159], v218 offset:9216
	ds_read_b128 v[152:155], v218 offset:11264
	ds_read_b128 v[148:151], v218 offset:13312
	ds_read_b128 v[144:147], v218 offset:15360
	s_setprio 1
	s_waitcnt lgkmcnt(0)
	v_mfma_f32_16x16x32_bf16 v[0:3], v[64:67], v[12:15], v[48:51]
	v_mfma_f32_16x16x32_bf16 v[4:7], v[68:71], v[12:15], v[52:55]
	v_mfma_f32_16x16x32_bf16 v[8:11], v[76:79], v[12:15], v[56:59]
	v_mfma_f32_16x16x32_bf16 v[12:15], v[72:75], v[12:15], v[60:63]
	v_mfma_f32_16x16x32_bf16 v[16:19], v[64:67], v[242:245], v[162:165]
	v_mfma_f32_16x16x32_bf16 v[20:23], v[68:71], v[242:245], v[166:169]
	v_mfma_f32_16x16x32_bf16 v[24:27], v[76:79], v[242:245], v[170:173]
	v_mfma_f32_16x16x32_bf16 v[28:31], v[72:75], v[242:245], v[174:177]
	v_mfma_f32_16x16x32_bf16 v[32:35], v[64:67], v[246:249], v[178:181]
	v_mfma_f32_16x16x32_bf16 v[36:39], v[68:71], v[246:249], v[182:185]
	v_mfma_f32_16x16x32_bf16 v[40:43], v[76:79], v[246:249], v[186:189]
	v_mfma_f32_16x16x32_bf16 v[44:47], v[72:75], v[246:249], v[222:225]
	v_mfma_f32_16x16x32_bf16 v[48:51], v[64:67], v[214:217], v[226:229]
	v_mfma_f32_16x16x32_bf16 v[52:55], v[68:71], v[214:217], v[230:233]
	v_mfma_f32_16x16x32_bf16 v[56:59], v[76:79], v[214:217], v[234:237]
	v_mfma_f32_16x16x32_bf16 v[60:63], v[72:75], v[214:217], v[238:241]
	s_setprio 0
	v_lshlrev_b32_e32 v160, 8, v160
	s_movk_i32 s9, 0x8000
	v_readlane_b32 s4, v255, 10
	v_lshlrev_b32_e32 v162, 4, v200
	v_lshlrev_b32_e32 v164, 4, v201
	v_lshlrev_b32_e32 v167, 4, v204
	v_and_or_b32 v160, v160, s9, v191
	v_lshlrev_b32_e32 v166, 11, v161
	s_add_u32 s4, s4, s46
	v_readlane_b32 s5, v255, 7
	v_and_or_b32 v162, v162, s9, v191
	v_and_or_b32 v164, v164, s9, v191
	v_and_or_b32 v167, v167, s9, v191
	s_waitcnt lgkmcnt(0)
	v_or3_b32 v168, v160, v166, v190
	v_mov_b32_e32 v169, v193
	s_addc_u32 s5, s5, s47
	v_or3_b32 v170, v162, v166, v190
	v_mov_b32_e32 v171, v193
	v_or3_b32 v172, v164, v166, v190
	v_mov_b32_e32 v173, v193
	v_or3_b32 v174, v167, v166, v190
	v_mov_b32_e32 v175, v193
	s_waitcnt vmcnt(0)
	v_writelane_b32 v255, s52, 12
	v_writelane_b32 v255, s53, 13
	v_writelane_b32 v255, s64, 14
	v_writelane_b32 v255, s65, 15
	v_writelane_b32 v255, s30, 16
	s_mov_b64 s[64:65], s[4:5]
	s_add_u32 s4, s38, s36
	s_addc_u32 s5, s39, s37
	s_mov_b64 s[52:53], s[4:5]
	s_mov_b64 s[4:5], 0
	s_waitcnt vmcnt(0)
	v_lshrrev_b32_e32 v164, 6, v252
	v_lshlrev_b32_e32 v164, 10, v164
	s_nop 0
	v_readfirstlane_b32 s30, v164
	v_and_b32_e32 v165, 63, v252
	v_lshlrev_b32_e32 v165, 4, v165
	s_barrier
	s_and_b32 s9, s8, 0x10000
	v_add_u32_e32 v221, s9, v218
	v_or_b32_e32 v226, s9, v219
	s_xor_b32 s9, s9, 0x10000
	s_add_u32 s9, s9, s30
	.p2align	6
